# attention: one static priority raise for waves 4..7 over the four latent units
# baseline (speedup 1.0000x reference)
; __device__ __forceinline__ void attn_phase(ldsp lds, char* shm, const bf16_t* QKV, bf16_t* O, const int tid, const int bx) {
;     const int xcd = bx & 7, slot = bx >> 3;
;     typedef attn_body::bf16 abf;
;     for (int i = 0; i < 4; ++i) {
;         const int bk = 8 * i + xcd, b = bk >> 2, kvh = bk & 3, h = kvh * 4 + (slot >> 3), qb = slot & 7;
;     ...
;         attn_unit_simple(lds, QKV, O, b * SEQ + qb * 256, h, b * SEQ, 32, ML + b * CL, 36, tid);
;     ...
;         attn_body::attn_unit<8>((const abf*)(QKV + (size_t)(b * SEQ + qb * 256) * 1536 + h * 64), (const abf*)(QKV + 1024 + kvh * 64), b * SEQ, 32, ML + b * CL, 36,
;                                 (abf*)(O + (size_t)(b * SEQ + qb * 256) * D + h * 64), shm, tid);
;     ...
;     }
.LBB0_750:
	v_readfirstlane_b32 s0, v196
	s_cmp_lt_u32 s0, 0x100
	s_cbranch_scc1 .Latt_noprio
	s_setprio 1

; #define WAIT_BAR(N) asm volatile("s_waitcnt vmcnt(" #N ") lgkmcnt(0)\n\ts_barrier":::"memory")
;   #define DMA_K(t,slot) glds16(ksrc+TROW(t),(unsigned)__builtin_amdgcn_readfirstlane(kdst+(slot)))
;   #define DMA_V(t,slot) glds16(vsrc+TROW(t),(unsigned)__builtin_amdgcn_readfirstlane(vdst+(slot)))
; template<int THRL> __device__ __forceinline__ void attn_unit(const bf16*Qw0,const bf16*__restrict__ Kcol,int latrow0,int nlat,int ctxrow0,int NT,bf16*Ow0,char*shm,const int tid){
;   const int lane=tid&63,r32=lane&31,hi=lane>>5; const int wid=__builtin_amdgcn_readfirstlane(tid>>6);
;   const bf16*Qw=Qw0+(long)(wid*QBLK)*QP;
;   const unsigned lds0=(unsigned)(uintptr_t)shm;
;   float*wsf=(float*)(shm+LDS_WS)+wid*64;
;   const bf16*ksrc=Kcol+(long)lane*QP+wid*8;
;   const bf16*vsrc=Kcol+256+(long)(16*(wid&3)+(lane>>2))*QP+(wid>>2)*32+(lane&3)*8;
;     ...
;   const unsigned kdst=lds0+LDS_K+wid*1024, vdst=lds0+LDS_V+wid*1024;
;     ...
;   const int vb0=(int)(lds0+LDS_V)+((lane>>4)&1)*32+(lane&3)*8+(4*hi+((lane&15)>>2))*64;
;   const char*Kbase=shm+LDS_K; bf16x8 kf[8];
;   const lds_cptr shm3=(lds_cptr)shm; const lds_cptr kp0=shm3+LDS_K+hi*1024+r32*16; const lds_cptr vp0=shm3+LDS_V+((lane>>4)&1)*32+(lane&3)*8+(4*hi+((lane&15)>>2))*64;
;   DMA_K(0,0);DMA_V(0,0);DMA_K(1,SLOTB);
;   bf16x8 qr[4];
;   #pragma unroll
;   for(int d0=0;d0<4;++d0)qr[d0]=*reinterpret_cast<const bf16x8*>(&Qw[(long)r32*QP+d0*16+hi*8]);
;   float mhat=0.f,l_reg=0.f;f32x16 o[2];o[0]=f32x16{};o[1]=f32x16{};const f32x16 negm=f32x16{};
;     ...
;   bool resc=false;
;     ...
;   f32x16 pA0,pA1,pB0,pB1;
;   int sl_prev=0,sl_cur=0,sl_next=SLOTB;
;     ...
;   DMA_K(2,2*SLOTB);
;   WAIT_BAR(3);
;   qkt(pA0,pA1,Kbase,qr,negm,r32,hi);asm volatile("s_nop 15\n\ts_nop 7":"+v"(pA0),"+v"(pA1));CMASK(pA0,pA1,0);
;   START(pA0,pA1);
;   _Pragma("unroll") for(int r=0;r<16;++r)pA1[r]=__builtin_amdgcn_exp2f(pA1[r]);
;   WAIT_BAR(0);
;   DMA_K(3,0);DMA_V(1,SLOTB);
;   ROT();
;   kload8(kf,kp0+sl_cur);
;   WAIT_BAR(2);
; __device__ __forceinline__ void attn_phase(ldsp lds, char* shm, const bf16_t* QKV, bf16_t* O, const int tid, const int bx) {
;     ...
;     if (slot < 16) { const int b = xcd, h = slot;
;     ...
;         attn_unit_simple(lds, QKV, O, ML + b * CL, h, 0, 0, ML + b * CL, 4, tid);
;     ...
;         attn_body::attn_unit<8>((const abf*)(QKV + (size_t)(ML + b * CL) * 1536 + h * 64), (const abf*)(QKV + 1024 + (h >> 2) * 64), 0, 0, ML + b * CL, 4,
.LBB0_797:
	s_setprio 0
	s_cmp_lt_i32 s17, 16
	s_cbranch_scc0 .LBB0_810
	s_lshl_b32 s0, s96, 1
	s_and_b32 s8, s0, 0xffffffc0
	s_lshl_b32 s1, s16, 8
	s_lshl_b32 s6, s17, 6
	s_ashr_i32 s9, s8, 31
	s_bitset1_b32 s1, 14
	s_ashr_i32 s7, s6, 31
	s_lshl_b64 s[8:9], s[8:9], 1
	s_add_u32 s14, s22, s8
	s_mul_i32 s10, s16, 0xc0000
	s_mul_i32 s34, s1, 0xc00
	s_addc_u32 s15, s23, s9
	s_or_b32 s12, s10, 0x3030000
	v_readlane_b32 s8, v254, 37
	v_readlane_b32 s9, v254, 38
	s_add_u32 s0, s8, s34
	s_addc_u32 s3, s9, 0
	s_lshl_b64 s[8:9], s[6:7], 1
	s_add_u32 s6, s0, s8
	s_addc_u32 s7, s3, s9
	v_readfirstlane_b32 s3, v196
	s_ashr_i32 s0, s3, 6
	s_lshl_b32 s11, s0, 4
	v_and_or_b32 v4, s11, 48, v234
	v_mov_b32_e32 v199, v97
	v_mul_u32_u24_e32 v4, 0x600, v4
	v_lshlrev_b32_e32 v0, 1, v190
	v_mov_b32_e32 v1, v97
	v_lshl_add_u64 v[2:3], s[6:7], 0, v[198:199]
	s_and_b32 s7, s3, 0x3fffffc0
	v_lshlrev_b32_e32 v4, 1, v4
	v_mov_b32_e32 v5, v97
	s_ashr_i32 s3, s3, 3
	v_lshl_add_u64 v[0:1], s[14:15], 0, v[0:1]
	s_lshl_b32 s16, s0, 3
	v_lshl_add_u64 v[4:5], s[14:15], 0, v[4:5]
	s_and_b32 s14, s3, 0xffffffe0
	s_lshl_b32 s6, s0, 5
	s_ashr_i32 s17, s16, 31
	s_ashr_i32 s15, s14, 31
	s_lshl_b32 s3, s0, 10
	v_lshl_add_u64 v[4:5], s[14:15], 1, v[4:5]
	v_mov_b32_e32 v193, v97
	s_cmp_lg_u32 0, -1
	v_lshl_add_u64 v[0:1], s[16:17], 1, v[0:1]
	v_lshl_add_u64 v[36:37], v[4:5], 0, v[192:193]
	s_mov_b64 s[14:15], 0x200
	s_cselect_b32 s11, 0, 0
	v_lshl_add_u64 v[38:39], v[36:37], 0, s[14:15]
	s_add_i32 s14, s11, s3
	v_lshl_add_u64 v[4:5], v[0:1], 0, s[34:35]
	s_mov_b32 s11, m0
	s_mov_b32 m0, s14
	s_nop 0
	global_load_lds_dwordx4 v[4:5], off
	s_mov_b32 m0, s11
	s_mov_b32 s13, s35
	s_add_i32 s3, s14, 0x6000
	v_lshl_add_u64 v[4:5], v[38:39], 0, s[34:35]
	s_mov_b32 s11, m0
	s_mov_b32 m0, s3
	s_nop 0
	global_load_lds_dwordx4 v[4:5], off
	s_mov_b32 m0, s11
	v_lshl_add_u64 v[4:5], v[0:1], 0, s[12:13]
	s_add_i32 s11, s14, 0x2000
	s_mov_b32 s15, m0
	s_mov_b32 m0, s11
	s_nop 0
	global_load_lds_dwordx4 v[4:5], off
	s_mov_b32 m0, s15
	v_mad_i64_i32 v[2:3], s[16:17], s6, v224, v[2:3]
	global_load_dwordx4 v[126:129], v[2:3], off
	global_load_dwordx4 v[122:125], v[2:3], off offset:32
	global_load_dwordx4 v[118:121], v[2:3], off offset:64
	global_load_dwordx4 v[114:117], v[2:3], off offset:96
	s_mov_b32 s11, s35
	v_lshl_add_u64 v[40:41], v[0:1], 0, s[10:11]
	s_mov_b64 s[16:17], 0x3060000
	v_lshl_add_u64 v[0:1], v[40:41], 0, s[16:17]
	s_add_i32 s15, s14, 0x4000
	s_mov_b32 s16, m0
	s_mov_b32 m0, s15
	s_nop 0
	global_load_lds_dwordx4 v[0:1], off
	s_mov_b32 m0, s16
	s_waitcnt vmcnt(3) lgkmcnt(0)
	s_barrier
	ds_read_b128 v[0:3], v231
	ds_read_b128 v[16:19], v231 offset:512
	ds_read_b128 v[32:35], v231 offset:2048
	s_mov_b64 s[16:17], 0x3090000
	s_lshl_b32 s7, s7, 2
	s_add_i32 s7, s7, 0
	v_lshl_add_u32 v172, v233, 2, s7
	s_waitcnt vmcnt(3) lgkmcnt(2)
	v_mfma_f32_32x32x16_bf16 v[0:15], v[0:3], v[126:129], 0
	s_waitcnt vmcnt(2) lgkmcnt(0)
	v_mfma_f32_32x32x16_bf16 v[0:15], v[32:35], v[122:125], v[0:15]
	ds_read_b128 v[32:35], v231 offset:2560
	v_mfma_f32_32x32x16_bf16 v[16:31], v[16:19], v[126:129], 0
	s_waitcnt lgkmcnt(0)
	v_mfma_f32_32x32x16_bf16 v[16:31], v[32:35], v[122:125], v[16:31]
	ds_read_b128 v[32:35], v231 offset:4096
	s_waitcnt vmcnt(1) lgkmcnt(0)
	v_mfma_f32_32x32x16_bf16 v[0:15], v[32:35], v[118:121], v[0:15]
	ds_read_b128 v[32:35], v231 offset:4608
	s_waitcnt lgkmcnt(0)
	v_mfma_f32_32x32x16_bf16 v[16:31], v[32:35], v[118:121], v[16:31]
	ds_read_b128 v[32:35], v231 offset:6144
	s_waitcnt vmcnt(0) lgkmcnt(0)
	v_mfma_f32_32x32x16_bf16 v[0:15], v[32:35], v[114:117], v[0:15]
	ds_read_b128 v[32:35], v231 offset:6656
	s_waitcnt lgkmcnt(0)
	v_mfma_f32_32x32x16_bf16 v[16:31], v[32:35], v[114:117], v[16:31]
	s_nop 15
	s_nop 7
	s_waitcnt vmcnt(0) lgkmcnt(0)
	s_barrier
	s_nop 0
	v_max3_f32 v32, v0, v1, v16
	v_max3_f32 v33, v2, v3, v17
	s_nop 0
	v_max3_f32 v32, v32, v18, v19
	v_max3_f32 v33, v33, v6, v7
	s_nop 0
	v_max3_f32 v32, v32, v4, v5
	v_max3_f32 v33, v33, v22, v23
	s_nop 0
	v_max3_f32 v32, v32, v20, v21
	v_max3_f32 v33, v33, v10, v11
	s_nop 0
	v_max3_f32 v32, v32, v8, v9
	v_max3_f32 v33, v33, v26, v27
	s_nop 0
	v_max3_f32 v32, v32, v24, v25
	v_max3_f32 v33, v33, v14, v15
	s_nop 0
	v_max3_f32 v32, v32, v12, v13
	v_max3_f32 v33, v33, v30, v31
	s_nop 0
	v_max3_f32 v32, v32, v28, v29
	s_nop 0
	v_max_f32_e32 v32, v32, v33
	s_nop 0
	v_mov_b32_e32 v33, v32
	s_nop 1
	v_permlane32_swap_b32_e32 v32, v33
	v_max_f32_e32 v32, v32, v33
	s_nop 0
	v_sub_f32_e32 v0, v0, v32
	v_sub_f32_e32 v1, v1, v32
	v_add_f32_e32 v170, v97, v32
	v_sub_f32_e32 v16, v16, v32
	v_sub_f32_e32 v17, v17, v32
	v_sub_f32_e32 v2, v2, v32
	v_sub_f32_e32 v18, v18, v32
	v_sub_f32_e32 v3, v3, v32
	v_sub_f32_e32 v19, v19, v32
	v_sub_f32_e32 v4, v4, v32
	v_sub_f32_e32 v20, v20, v32
	v_sub_f32_e32 v5, v5, v32
	v_sub_f32_e32 v21, v21, v32
	v_sub_f32_e32 v6, v6, v32
	v_sub_f32_e32 v22, v22, v32
	v_sub_f32_e32 v7, v7, v32
	v_sub_f32_e32 v23, v23, v32
	v_sub_f32_e32 v8, v8, v32
	v_sub_f32_e32 v24, v24, v32
	v_sub_f32_e32 v9, v9, v32
	v_sub_f32_e32 v25, v25, v32
	v_sub_f32_e32 v10, v10, v32
	v_sub_f32_e32 v26, v26, v32
	v_sub_f32_e32 v11, v11, v32
	v_sub_f32_e32 v27, v27, v32
	v_sub_f32_e32 v12, v12, v32
	v_sub_f32_e32 v28, v28, v32
	v_sub_f32_e32 v13, v13, v32
	v_sub_f32_e32 v29, v29, v32
	v_sub_f32_e32 v14, v14, v32
	v_sub_f32_e32 v30, v30, v32
	v_sub_f32_e32 v15, v15, v32
	v_sub_f32_e32 v31, v31, v32
	s_nop 0
	v_exp_f32_e32 v32, v0
	v_exp_f32_e32 v33, v1
	v_lshl_add_u64 v[0:1], v[40:41], 0, s[16:17]
	s_mov_b32 s15, m0
	s_mov_b32 m0, s14
	s_nop 0
	global_load_lds_dwordx4 v[0:1], off
	s_mov_b32 m0, s15
	v_lshl_add_u64 v[0:1], v[38:39], 0, s[12:13]
	s_add_i32 s12, s14, 0x8000
	s_mov_b32 s13, m0
	s_mov_b32 m0, s12
	s_nop 0
	global_load_lds_dwordx4 v[0:1], off
	s_mov_b32 m0, s13
	v_exp_f32_e32 v34, v2
	v_exp_f32_e32 v35, v3
	v_exp_f32_e32 v74, v16
	v_exp_f32_e32 v75, v17
	v_exp_f32_e32 v92, v18
	v_exp_f32_e32 v93, v19
	ds_read_b128 v[0:3], v231 offset:8192
	ds_read_b128 v[16:19], v231 offset:8704
	ds_read_b128 v[38:41], v231 offset:10240
	ds_read_b128 v[42:45], v231 offset:10752
	ds_read_b128 v[46:49], v231 offset:12288
	ds_read_b128 v[50:53], v231 offset:12800
	ds_read_b128 v[54:57], v231 offset:14336
	ds_read_b128 v[58:61], v231 offset:14848
	v_exp_f32_e32 v62, v4
	v_exp_f32_e32 v63, v5
	v_exp_f32_e32 v64, v6
	v_exp_f32_e32 v65, v7
	v_exp_f32_e32 v66, v8
	v_exp_f32_e32 v67, v9
	v_exp_f32_e32 v68, v10
	v_exp_f32_e32 v69, v11
	v_exp_f32_e32 v70, v12
	v_exp_f32_e32 v71, v13
	v_exp_f32_e32 v72, v14
	v_exp_f32_e32 v73, v15
	v_exp_f32_e32 v94, v20
	v_exp_f32_e32 v95, v21
	v_exp_f32_e32 v110, v22
	v_exp_f32_e32 v111, v23
	v_exp_f32_e32 v112, v24
	v_exp_f32_e32 v113, v25
	s_waitcnt vmcnt(2) lgkmcnt(0)
	s_barrier
	v_exp_f32_e32 v130, v26
	v_exp_f32_e32 v131, v27
	v_exp_f32_e32 v132, v28
	v_exp_f32_e32 v133, v29
	v_exp_f32_e32 v134, v30
	v_exp_f32_e32 v135, v31
	ds_read_b64_tr_b16 v[84:85], v230 offset:24576
	ds_read_b64_tr_b16 v[86:87], v230 offset:25088
	v_add_f32_e32 v4, v32, v33
	v_add_f32_e32 v4, v4, v34
	v_add_f32_e32 v4, v4, v35
	v_add_f32_e32 v4, v4, v62
	v_add_f32_e32 v20, v4, v63
	s_waitcnt lgkmcnt(9)
	v_mfma_f32_32x32x16_bf16 v[0:15], v[0:3], v[126:129], 0
	v_cvt_pk_bf16_f32 v106, v32, v33
	v_cvt_pk_bf16_f32 v107, v34, v35
	ds_read_b64_tr_b16 v[80:81], v230 offset:28672
	ds_read_b64_tr_b16 v[82:83], v230 offset:29184
	v_add_f32_e32 v20, v64, v20
	v_add_f32_e32 v20, v65, v20
	v_add_f32_e32 v20, v66, v20
	v_add_f32_e32 v76, v67, v20
	v_cvt_pk_bf16_f32 v108, v62, v63
	v_cvt_pk_bf16_f32 v109, v64, v65
	s_waitcnt lgkmcnt(10)
	v_mfma_f32_32x32x16_bf16 v[16:31], v[16:19], v[126:129], 0
	ds_read_b64_tr_b16 v[32:33], v230 offset:25600
	ds_read_b64_tr_b16 v[34:35], v230 offset:26112
	s_waitcnt lgkmcnt(11)
	v_mfma_f32_32x32x16_bf16 v[0:15], v[38:41], v[122:125], v[0:15]
	v_add_f32_e32 v38, v68, v76
	v_add_f32_e32 v38, v69, v38
	v_add_f32_e32 v38, v70, v38
	v_add_f32_e32 v38, v71, v38
	v_cvt_pk_bf16_f32 v102, v66, v67
	v_cvt_pk_bf16_f32 v103, v68, v69
	ds_read_b64_tr_b16 v[76:77], v230 offset:29696
	ds_read_b64_tr_b16 v[78:79], v230 offset:30208
	v_add_f32_e32 v38, v72, v38
	v_add_f32_e32 v38, v73, v38
	v_add_f32_e32 v38, v74, v38
	v_add_f32_e32 v38, v75, v38
	v_cvt_pk_bf16_f32 v104, v70, v71
	v_cvt_pk_bf16_f32 v105, v72, v73
	s_waitcnt lgkmcnt(12)
	v_mfma_f32_32x32x16_bf16 v[16:31], v[42:45], v[122:125], v[16:31]
	ds_read_b64_tr_b16 v[88:89], v230 offset:26624
	ds_read_b64_tr_b16 v[90:91], v230 offset:27136
	s_waitcnt lgkmcnt(13)
	v_mfma_f32_32x32x16_bf16 v[0:15], v[46:49], v[118:121], v[0:15]
	v_add_f32_e32 v38, v92, v38
	v_add_f32_e32 v38, v93, v38
	v_add_f32_e32 v38, v94, v38
	v_add_f32_e32 v38, v95, v38
	v_cvt_pk_bf16_f32 v98, v74, v75
	v_cvt_pk_bf16_f32 v99, v92, v93
	ds_read_b64_tr_b16 v[64:65], v230 offset:30720
	ds_read_b64_tr_b16 v[66:67], v230 offset:31232
	v_add_f32_e32 v38, v110, v38
	v_add_f32_e32 v38, v111, v38
	v_add_f32_e32 v38, v112, v38
	v_add_f32_e32 v38, v113, v38
	v_cvt_pk_bf16_f32 v100, v94, v95
	v_cvt_pk_bf16_f32 v101, v110, v111
	s_waitcnt lgkmcnt(14)
	v_mfma_f32_32x32x16_bf16 v[16:31], v[50:53], v[118:121], v[16:31]
	ds_read_b64_tr_b16 v[68:69], v230 offset:27648
	ds_read_b64_tr_b16 v[70:71], v230 offset:28160
	s_waitcnt lgkmcnt(14)
	v_mfma_f32_32x32x16_bf16 v[0:15], v[54:57], v[114:117], v[0:15]
	v_add_f32_e32 v38, v130, v38
	v_add_f32_e32 v38, v131, v38
	v_add_f32_e32 v38, v132, v38
	v_add_f32_e32 v38, v133, v38
	v_cvt_pk_bf16_f32 v110, v112, v113
	v_cvt_pk_bf16_f32 v111, v130, v131
	ds_read_b64_tr_b16 v[72:73], v230 offset:31744
	ds_read_b64_tr_b16 v[74:75], v230 offset:32256
	v_add_f32_e32 v38, v134, v38
	v_add_f32_e32 v38, v135, v38
	v_add_f32_e32 v38, 0, v38
	v_cvt_pk_bf16_f32 v112, v132, v133
	v_cvt_pk_bf16_f32 v113, v134, v135
	v_mfma_f32_32x32x16_bf16 v[16:31], v[58:61], v[114:117], v[16:31]
	v_add_f32_e64 v0, v0, -v170
	v_add_f32_e64 v1, v1, -v170
	v_lshl_add_u64 v[92:93], v[36:37], 0, s[10:11]
	s_mov_b64 s[10:11], 0x3060200
	s_nop 7
	v_pk_add_f32 v[94:95], v[16:17], v[170:171] op_sel_hi:[1,0] neg_lo:[0,1] neg_hi:[0,1]
	v_pk_add_f32 v[2:3], v[2:3], v[170:171] op_sel_hi:[1,0] neg_lo:[0,1] neg_hi:[0,1]
	v_pk_add_f32 v[138:139], v[18:19], v[170:171] op_sel_hi:[1,0] neg_lo:[0,1] neg_hi:[0,1]
	v_pk_add_f32 v[52:53], v[4:5], v[170:171] op_sel_hi:[1,0] neg_lo:[0,1] neg_hi:[0,1]
	v_max_f32_e32 v4, v0, v1
	v_lshl_add_u64 v[36:37], v[92:93], 0, s[10:11]
	v_pk_add_f32 v[54:55], v[6:7], v[170:171] op_sel_hi:[1,0] neg_lo:[0,1] neg_hi:[0,1]
	v_max3_f32 v5, v2, v3, v95
	v_max3_f32 v4, v4, v94, v138
	v_add_f32_e32 v166, 0, v38
	s_add_i32 s10, s14, 0xa000
	s_mov_b32 s11, m0
	s_mov_b32 m0, s10
	s_nop 0
	global_load_lds_dwordx4 v[36:37], off
	s_mov_b32 m0, s11
	v_pk_add_f32 v[36:37], v[20:21], v[170:171] op_sel_hi:[1,0] neg_lo:[0,1] neg_hi:[0,1]
	v_pk_add_f32 v[38:39], v[22:23], v[170:171] op_sel_hi:[1,0] neg_lo:[0,1] neg_hi:[0,1]
	v_max3_f32 v4, v4, v139, v52
	v_max3_f32 v5, v5, v54, v55
	v_pk_add_f32 v[56:57], v[8:9], v[170:171] op_sel_hi:[1,0] neg_lo:[0,1] neg_hi:[0,1]
	v_pk_add_f32 v[58:59], v[10:11], v[170:171] op_sel_hi:[1,0] neg_lo:[0,1] neg_hi:[0,1]
	v_max3_f32 v4, v4, v53, v36
	v_max3_f32 v5, v5, v38, v39
	v_pk_add_f32 v[40:41], v[24:25], v[170:171] op_sel_hi:[1,0] neg_lo:[0,1] neg_hi:[0,1]
	v_pk_add_f32 v[42:43], v[26:27], v[170:171] op_sel_hi:[1,0] neg_lo:[0,1] neg_hi:[0,1]
	v_max3_f32 v4, v4, v37, v56
	v_max3_f32 v5, v5, v58, v59
	v_pk_add_f32 v[60:61], v[12:13], v[170:171] op_sel_hi:[1,0] neg_lo:[0,1] neg_hi:[0,1]
	v_pk_add_f32 v[62:63], v[14:15], v[170:171] op_sel_hi:[1,0] neg_lo:[0,1] neg_hi:[0,1]
	v_max3_f32 v4, v4, v57, v40
	v_max3_f32 v5, v5, v42, v43
	v_pk_add_f32 v[44:45], v[28:29], v[170:171] op_sel_hi:[1,0] neg_lo:[0,1] neg_hi:[0,1]
	v_pk_add_f32 v[46:47], v[30:31], v[170:171] op_sel_hi:[1,0] neg_lo:[0,1] neg_hi:[0,1]
	v_max3_f32 v4, v4, v41, v60
	v_max3_f32 v5, v5, v62, v63
	v_max3_f32 v4, v4, v61, v44
	v_max3_f32 v5, v5, v46, v47
	v_max3_f32 v4, v4, v45, v5
	v_mov_b32_e32 v5, v4
	s_nop 1
	v_permlane32_swap_b32_e32 v4, v5
	v_max_f32_e32 v5, v5, v5
	v_max_f32_e32 v4, v4, v4
	v_max_f32_e32 v4, v4, v5
	v_cmp_lt_f32_e32 vcc, s64, v4
	s_cmp_lg_u64 vcc, 0
	s_cselect_b64 s[10:11], -1, 0
	s_cbranch_vccnz .LBB0_1282
